# GQA attention loop: K and V^T tiles go HBM->LDS directly (global_load_lds_dwordx4) into an unpadded XOR-swizzled image (swizzle on the source address, mirrored on ds_read); no register staging / ds_wr
# speedup vs baseline: 1.0614x; 1.0127x over previous
; DI unsigned pack2(float a, float b) { f32x2v f = {a, b}; bf16x2v v = __builtin_convertvector(f, bf16x2v); return __builtin_bit_cast(unsigned, v); }
; DI int crow(int i, int h) { return (i & 3) + 8 * (i >> 2) + 4 * h; }
; DI int swap23(int r) { return (r & 0x13) | ((r & 4) << 1) | ((r & 8) >> 1); }
;   template <int PAR>
;   DI void step(int t, f32x16 (&cur)[2], f32x16 (&nxt)[2]) {
;     if (t + 1 < nt) sstore_k(PAR ^ 1);
;     if (t > 0) sstore_v(PAR);
;     __syncthreads();
;     if (t + 1 < nt) qk(PAR ^ 1, nxt);
;     float mx = fmaxf(cur[0][0], cur[1][0]);
; #pragma unroll
;     for (int i = 1; i < 16; ++i) mx = fmaxf(fmaxf(cur[0][i], cur[1][i]), mx);
;     if (__builtin_amdgcn_ballot_w64(mx > ATT_THR) != 0ull) {
;       asm volatile("" ::: "memory");
;       mx = fmaxf(mx, xhalf(mx));
;       const float want = mref + fmaxf(mx, 0.f);
;       const float mn = __uint_as_float(pack2(want, 0.f) << 16);
;       const float d = mn - mref;
;       const float alpha = __builtin_amdgcn_exp2f(-d);
;       mref = mn;
;       l *= alpha;
; #pragma unroll
;       for (int a = 0; a < 2; ++a)
; #pragma unroll
;         for (int i = 0; i < 16; ++i) { o[a][i] *= alpha; cur[a][i] -= d; nxt[a][i] -= d; }
;       u32x4 q4 = {h == 0 ? (pack2(-mn, 0.f) & 0xffffu) : 0u, 0u, 0u, 0u};
;       qm = __builtin_bit_cast(bf16x8, q4);
;     }
;     float psum = 0.f;
; #pragma unroll
;     for (int kb2 = 0; kb2 < 2; ++kb2)
; #pragma unroll
;       for (int i = 0; i < 16; ++i) { const float pv = __builtin_amdgcn_exp2f(cur[kb2][i]); cur[kb2][i] = pv; psum += pv; }
;     l += psum;
;     if (t + 2 < nt) gload_k(t + 2);
;     if (t + 1 < nt) gload_v(t + 1);
; template <int DQK>
; DI void attn_item(const u16* __restrict__ Qb, int qpitch, const u16* __restrict__ Kb, int kpitch, const u16* __restrict__ KPEb,
;                   const u16* __restrict__ Vt, float* __restrict__ ssq, int rowq0, int rowk0, int nt, char* smem, int tid, bool dry) {
;     ...
;   c.gload_k(0); c.gload_v(0);
;   __syncthreads();
;   c.sstore_k(0); c.sstore_v(0);
;   if (nt > 1) c.gload_k(1);
;   __syncthreads();
;   c.qk(0, sa);
; #pragma unroll
;   for (int i = 0; i < 16; ++i) {
;     sa[0][i] = -1e30f;
;     if (swap23(crow(i, h)) < 16) sa[1][i] = -1e30f;
;   }
;   int t = 0;
;   for (; t + 1 < nt; t += 2) {
;     c.template step<0>(t, sa, sb);
;     c.template step<1>(t + 1, sb, sa);
.Lg_entry:
	v_mov_b32_e32 v169, 0
	v_mov_b32_e32 v170, 0
	v_mov_b32_e32 v171, 0
	v_mov_b32_e32 v182, 0
	v_mov_b32_e32 v183, 0
	s_waitcnt vmcnt(0)
	v_lshrrev_b32_e32 v100, 3, v245
	v_and_b32_e32 v101, 7, v245
	v_bfe_u32 v102, v245, 4, 3
	v_xor_b32_e32 v101, v101, v102
	v_lshlrev_b32_e32 v101, 4, v101
	v_lshl_add_u32 v100, v100, 7, v101
	ds_write_b128 v100, v[152:155] offset:9216
	ds_write_b128 v100, v[156:159] offset:13312
	ds_write_b128 v100, v[160:163] offset:18432
	ds_write_b128 v100, v[164:167] offset:22528
	v_readfirstlane_b32 s47, v245
	s_nop 3
	s_lshr_b32 s47, s47, 6
	s_lshl_b32 s1, s47, 4
	v_lshrrev_b32_e32 v101, 3, v227
	v_lshrrev_b32_e32 v102, 4, v227
	v_and_b32_e32 v103, 7, v227
	v_xor_b32_e32 v103, v103, v102
	v_lshlrev_b32_e32 v103, 4, v103
	v_xor_b32_e32 v102, 64, v103
	v_add_u32_e32 v101, s1, v101
	v_lshl_add_u32 v104, v101, 8, v103
	v_lshl_add_u32 v106, v101, 8, v102
	v_add_u32_e32 v106, 0x400, v106
	v_mov_b32_e32 v105, 0
	v_mov_b32_e32 v107, 0
	v_mul_u32_u24_e32 v108, 0x20600, v101
	v_add_u32_e32 v110, v108, v102
	v_add_u32_e32 v108, v108, v103
	v_add_u32_e32 v110, 0x102c00, v110
	v_mov_b32_e32 v109, 0
	v_mov_b32_e32 v111, 0
	s_sub_i32 s0, s46, 64
	s_ashr_i32 s1, s0, 31
	s_lshl_b64 s[0:1], s[0:1], 8
	s_add_u32 s0, s26, s0
	s_addc_u32 s1, s27, s1
	v_lshl_add_u64 v[214:215], v[104:105], 0, s[0:1]
	v_lshl_add_u64 v[216:217], v[106:107], 0, s[0:1]
	s_add_i32 s0, s46, 0xffffff80
	s_ashr_i32 s1, s0, 31
	s_lshl_b64 s[0:1], s[0:1], 1
	s_add_u32 s0, s30, s0
	s_addc_u32 s1, s31, s1
	v_lshl_add_u64 v[160:161], v[108:109], 0, s[0:1]
	v_lshl_add_u64 v[162:163], v[110:111], 0, s[0:1]
	s_add_u32 s0, s0, 0x80
	s_addc_u32 s1, s1, 0
	v_lshl_add_u64 v[164:165], v[108:109], 0, s[0:1]
	v_lshl_add_u64 v[166:167], v[110:111], 0, s[0:1]
	s_mov_b32 s20, 0x4000
	s_mov_b32 s21, 0
	s_lshl_b32 s46, s47, 11
	v_and_b32_e32 v100, 31, v227
	v_lshrrev_b32_e32 v101, 5, v227
	v_and_b32_e32 v102, 0x13, v100
	v_and_b32_e32 v103, 4, v100
	v_lshl_or_b32 v102, v103, 1, v102
	v_and_b32_e32 v103, 8, v100
	v_lshrrev_b32_e32 v103, 1, v103
	v_or_b32_e32 v102, v102, v103
	v_bfe_u32 v103, v102, 1, 3
	v_bfe_u32 v104, v100, 1, 3
	v_or_b32_e32 v105, 0, v101
	v_xor_b32_e32 v106, v105, v103
	v_lshlrev_b32_e32 v106, 4, v106
	v_lshl_add_u32 v152, v102, 7, v106
	v_xor_b32_e32 v106, v105, v104
	v_lshlrev_b32_e32 v106, 4, v106
	v_lshl_add_u32 v156, v100, 7, v106
	v_or_b32_e32 v105, 2, v101
	v_xor_b32_e32 v106, v105, v103
	v_lshlrev_b32_e32 v106, 4, v106
	v_lshl_add_u32 v153, v102, 7, v106
	v_xor_b32_e32 v106, v105, v104
	v_lshlrev_b32_e32 v106, 4, v106
	v_lshl_add_u32 v157, v100, 7, v106
	v_or_b32_e32 v105, 4, v101
	v_xor_b32_e32 v106, v105, v103
	v_lshlrev_b32_e32 v106, 4, v106
	v_lshl_add_u32 v154, v102, 7, v106
	v_xor_b32_e32 v106, v105, v104
	v_lshlrev_b32_e32 v106, 4, v106
	v_lshl_add_u32 v158, v100, 7, v106
	v_or_b32_e32 v105, 6, v101
	v_xor_b32_e32 v106, v105, v103
	v_lshlrev_b32_e32 v106, 4, v106
	v_lshl_add_u32 v155, v102, 7, v106
	v_xor_b32_e32 v106, v105, v104
	v_lshlrev_b32_e32 v106, 4, v106
	v_lshl_add_u32 v159, v100, 7, v106
	s_waitcnt lgkmcnt(0)
	s_barrier
	s_mov_b32 m0, s46
	s_nop 0
	global_load_lds_dwordx4 v[214:215], off
	global_load_lds_dwordx4 v[216:217], off offset:1024
	v_lshl_add_u64 v[214:215], v[214:215], 0, s[20:21]
	v_lshl_add_u64 v[216:217], v[216:217], 0, s[20:21]
	ds_read_b128 v[96:99], v152 offset:9216
	ds_read_b128 v[100:103], v152 offset:13312
	ds_read_b128 v[104:107], v153 offset:9216
	ds_read_b128 v[108:111], v153 offset:13312
	ds_read_b128 v[112:115], v154 offset:9216
	ds_read_b128 v[116:119], v154 offset:13312
	ds_read_b128 v[120:123], v155 offset:9216
	ds_read_b128 v[124:127], v155 offset:13312
	v_max3_f32 v128, v48, v32, v49
	v_max3_f32 v172, v33, v50, v34
	v_max3_f32 v128, v51, v35, v128
	v_max3_f32 v172, v52, v36, v172
	v_max3_f32 v128, v53, v37, v128
	v_max3_f32 v172, v54, v38, v172
	v_max3_f32 v128, v55, v39, v128
	v_max3_f32 v172, v56, v40, v172
	v_max3_f32 v128, v57, v41, v128
	v_max3_f32 v172, v58, v42, v172
	v_max3_f32 v128, v59, v43, v128
	v_max3_f32 v172, v60, v44, v172
	v_max3_f32 v128, v61, v45, v128
	v_max3_f32 v172, v62, v46, v172
	v_max3_f32 v128, v63, v47, v128
	v_max_f32_e32 v128, v128, v172
	v_and_b32_e32 v179, 0x7fff, v168
	v_cmp_ne_u32_e32 vcc, 0, v179
	s_cbranch_vccnz .LBB0_238
.Lgf_top:
	v_cmp_lt_f32_e32 vcc, s65, v128
	s_cbranch_vccnz .Lgf_rareA
.Lgf_rareA_ret:
	v_exp_f32_e32 v48, v48
	v_exp_f32_e32 v49, v49
	v_exp_f32_e32 v50, v50
	v_add_f32_e32 v182, v48, v182
	v_exp_f32_e32 v51, v51
	v_add_f32_e32 v183, v49, v183
	v_exp_f32_e32 v52, v52
	v_add_f32_e32 v182, v50, v182
	s_waitcnt lgkmcnt(7)
	v_mfma_f32_32x32x16_bf16 v[80:95], v[96:99], v[136:139], 0
	v_exp_f32_e32 v53, v53
	v_add_f32_e32 v183, v51, v183
	v_exp_f32_e32 v54, v54
	v_add_f32_e32 v182, v52, v182
	v_exp_f32_e32 v55, v55
	v_add_f32_e32 v183, v53, v183
	s_waitcnt lgkmcnt(6)
	v_mfma_f32_32x32x16_bf16 v[64:79], v[100:103], v[136:139], 0
	v_cvt_pk_bf16_f32 v48, v48, v49
	v_add_f32_e32 v182, v54, v182
	v_cvt_pk_bf16_f32 v49, v50, v51
	v_add_f32_e32 v183, v55, v183
	v_cvt_pk_bf16_f32 v50, v52, v53
	v_cvt_pk_bf16_f32 v51, v54, v55
	s_waitcnt lgkmcnt(5)
	v_mfma_f32_32x32x16_bf16 v[80:95], v[104:107], v[140:143], v[80:95]
	v_exp_f32_e32 v56, v56
	v_exp_f32_e32 v57, v57
	v_exp_f32_e32 v58, v58
	v_add_f32_e32 v182, v56, v182
	v_exp_f32_e32 v59, v59
	v_add_f32_e32 v183, v57, v183
	s_waitcnt lgkmcnt(4)
	v_mfma_f32_32x32x16_bf16 v[64:79], v[108:111], v[140:143], v[64:79]
	v_exp_f32_e32 v60, v60
	v_add_f32_e32 v182, v58, v182
	v_exp_f32_e32 v61, v61
	v_add_f32_e32 v183, v59, v183
	v_exp_f32_e32 v62, v62
	v_add_f32_e32 v182, v60, v182
	s_waitcnt vmcnt(0)
	s_waitcnt lgkmcnt(0)
	s_barrier
	s_add_i32 s0, s45, -1
	s_cmp_ge_u32 s0, s19
	s_cselect_b64 s[14:15], -1, 0
	s_cmp_ge_u32 s45, s19
	s_cbranch_scc1 .Lgf_skipKA
	s_add_i32 m0, s46, 9216
	s_nop 0
	global_load_lds_dwordx4 v[214:215], off
	global_load_lds_dwordx4 v[216:217], off offset:1024
	v_lshl_add_u64 v[214:215], v[214:215], 0, s[20:21]
	v_lshl_add_u64 v[216:217], v[216:217], 0, s[20:21]
; #define MFMA(a, b, c) __builtin_amdgcn_mfma_f32_32x32x16_bf16((a), (b), (c), 0, 0, 0)
; DI unsigned pack2(float a, float b) { f32x2v f = {a, b}; bf16x2v v = __builtin_convertvector(f, bf16x2v); return __builtin_bit_cast(unsigned, v); }
;   DI void qk(int buf, f32x16 (&s)[2]) {
;     const u16* kb = sK + buf * KBUF + sr * KP + h * 8;
; #pragma unroll
;     for (int kb2 = 0; kb2 < 2; ++kb2)
; #pragma unroll
;       for (int i = 0; i < 16; ++i) s[kb2][i] = 0.f;
; #pragma unroll
;     for (int ks = 0; ks < NKS; ++ks)
; #pragma unroll
;       for (int kb2 = 0; kb2 < 2; ++kb2) {
;         const bf16x8 a = *(const bf16x8*)(kb + kb2 * 32 * KP + ks * 16);
;         s[kb2] = MFMA(a, qf[ks], s[kb2]);
;       }
;     s[0] = MFMA(kone, qm, s[0]);
;     s[1] = MFMA(kone, qm, s[1]);
;   }
;   template <int PAR>
;   DI void step(int t, f32x16 (&cur)[2], f32x16 (&nxt)[2]) {
;     ...
;     float psum = 0.f;
; #pragma unroll
;     for (int kb2 = 0; kb2 < 2; ++kb2)
; #pragma unroll
;       for (int i = 0; i < 16; ++i) { const float pv = __builtin_amdgcn_exp2f(cur[kb2][i]); cur[kb2][i] = pv; psum += pv; }
;     l += psum;
;     if (t + 2 < nt) gload_k(t + 2);
;     if (t + 1 < nt) gload_v(t + 1);
;     const u16* vb = sV + PAR * VBUF + r * GP + h * 8;
; #pragma unroll
;     for (int kb2 = 0; kb2 < 2; ++kb2)
; #pragma unroll
;       for (int s2 = 0; s2 < 2; ++s2) {
;         u32x4 pk = {pack2(cur[kb2][8 * s2], cur[kb2][8 * s2 + 1]), pack2(cur[kb2][8 * s2 + 2], cur[kb2][8 * s2 + 3]),
;                     pack2(cur[kb2][8 * s2 + 4], cur[kb2][8 * s2 + 5]), pack2(cur[kb2][8 * s2 + 6], cur[kb2][8 * s2 + 7])};
;         const bf16x8 pf = __builtin_bit_cast(bf16x8, pk);
; #pragma unroll
;         for (int db = 0; db < 2; ++db) {
;           const bf16x8 a = *(const bf16x8*)(vb + db * 32 * GP + kb2 * 32 + s2 * 16);
;           o[db] = MFMA(a, pf, o[db]);
;         }
;       }
.Lgf_skipKA:
	s_add_i32 m0, s46, 27648
	s_nop 0
	global_load_lds_dwordx4 v[160:161], off
	global_load_lds_dwordx4 v[162:163], off offset:1024
	v_lshl_add_u64 v[160:161], v[160:161], 0, s[84:85]
	v_lshl_add_u64 v[162:163], v[162:163], 0, s[84:85]
	ds_read_b128 v[96:99], v156 offset:18432
	ds_read_b128 v[100:103], v156 offset:22528
	ds_read_b128 v[104:107], v157 offset:18432
	ds_read_b128 v[108:111], v157 offset:22528
	v_mfma_f32_32x32x16_bf16 v[80:95], v[112:115], v[144:147], v[80:95]
	ds_read_b128 v[112:115], v158 offset:18432
	v_exp_f32_e32 v63, v63
	v_add_f32_e32 v183, v61, v183
	v_cvt_pk_bf16_f32 v56, v56, v57
	v_add_f32_e32 v182, v62, v182
	v_cvt_pk_bf16_f32 v57, v58, v59
	v_add_f32_e32 v183, v63, v183
	v_mfma_f32_32x32x16_bf16 v[64:79], v[116:119], v[144:147], v[64:79]
	ds_read_b128 v[116:119], v158 offset:22528
	v_cvt_pk_bf16_f32 v58, v60, v61
	v_cvt_pk_bf16_f32 v59, v62, v63
	v_exp_f32_e32 v32, v32
	v_exp_f32_e32 v33, v33
	v_exp_f32_e32 v34, v34
	v_add_f32_e32 v182, v32, v182
	v_mfma_f32_32x32x16_bf16 v[80:95], v[120:123], v[148:151], v[80:95]
	ds_read_b128 v[120:123], v159 offset:18432
	v_exp_f32_e32 v35, v35
	v_add_f32_e32 v183, v33, v183
	v_exp_f32_e32 v36, v36
	v_add_f32_e32 v182, v34, v182
	v_exp_f32_e32 v37, v37
	v_add_f32_e32 v183, v35, v183
	v_mfma_f32_32x32x16_bf16 v[64:79], v[124:127], v[148:151], v[64:79]
	ds_read_b128 v[124:127], v159 offset:22528
	v_exp_f32_e32 v38, v38
	v_add_f32_e32 v182, v36, v182
	v_exp_f32_e32 v39, v39
	v_add_f32_e32 v183, v37, v183
	v_cvt_pk_bf16_f32 v32, v32, v33
	v_add_f32_e32 v182, v38, v182
	s_waitcnt lgkmcnt(7)
	v_mfma_f32_32x32x16_bf16 v[16:31], v[96:99], v[48:51], v[16:31]
	ds_read_b128 v[96:99], v152
	v_cvt_pk_bf16_f32 v33, v34, v35
	v_add_f32_e32 v183, v39, v183
	v_cvt_pk_bf16_f32 v34, v36, v37
	v_cvt_pk_bf16_f32 v35, v38, v39
	v_exp_f32_e32 v40, v40
	s_waitcnt lgkmcnt(7)
	v_mfma_f32_32x32x16_bf16 v[0:15], v[100:103], v[48:51], v[0:15]
	ds_read_b128 v[100:103], v152 offset:4096
	v_exp_f32_e32 v41, v41
	v_exp_f32_e32 v42, v42
	v_add_f32_e32 v182, v40, v182
	v_exp_f32_e32 v43, v43
	v_add_f32_e32 v183, v41, v183
	s_waitcnt lgkmcnt(7)
	v_mfma_f32_32x32x16_bf16 v[16:31], v[104:107], v[56:59], v[16:31]
	ds_read_b128 v[104:107], v153
	v_exp_f32_e32 v44, v44
	v_add_f32_e32 v182, v42, v182
	v_exp_f32_e32 v45, v45
	v_add_f32_e32 v183, v43, v183
	v_exp_f32_e32 v46, v46
	s_waitcnt lgkmcnt(7)
	v_mfma_f32_32x32x16_bf16 v[0:15], v[108:111], v[56:59], v[0:15]
	ds_read_b128 v[108:111], v153 offset:4096
	v_add_f32_e32 v182, v44, v182
	v_exp_f32_e32 v47, v47
	v_add_f32_e32 v183, v45, v183
	v_cvt_pk_bf16_f32 v40, v40, v41
	v_add_f32_e32 v182, v46, v182
	s_waitcnt lgkmcnt(7)
	v_mfma_f32_32x32x16_bf16 v[16:31], v[112:115], v[32:35], v[16:31]
	ds_read_b128 v[112:115], v154
	v_cvt_pk_bf16_f32 v41, v42, v43
	v_add_f32_e32 v183, v47, v183
	v_cvt_pk_bf16_f32 v42, v44, v45
	v_cvt_pk_bf16_f32 v43, v46, v47
	v_max3_f32 v128, v80, v64, v81
	s_waitcnt lgkmcnt(7)
	v_mfma_f32_32x32x16_bf16 v[0:15], v[116:119], v[32:35], v[0:15]
	ds_read_b128 v[116:119], v154 offset:4096
	v_max3_f32 v172, v65, v82, v66
	v_max3_f32 v128, v83, v67, v128
	v_max3_f32 v172, v84, v68, v172
	v_max3_f32 v128, v85, v69, v128
	v_max3_f32 v172, v86, v70, v172
	s_waitcnt lgkmcnt(7)
	v_mfma_f32_32x32x16_bf16 v[16:31], v[120:123], v[40:43], v[16:31]
	ds_read_b128 v[120:123], v155
	v_max3_f32 v128, v87, v71, v128
	v_max3_f32 v172, v88, v72, v172
	v_max3_f32 v128, v89, v73, v128
	v_max3_f32 v172, v90, v74, v172
	v_max3_f32 v128, v91, v75, v128
	s_waitcnt lgkmcnt(7)
	v_mfma_f32_32x32x16_bf16 v[0:15], v[124:127], v[40:43], v[0:15]
	ds_read_b128 v[124:127], v155 offset:4096
	v_max3_f32 v172, v92, v76, v172
	v_max3_f32 v128, v93, v77, v128
	v_max3_f32 v172, v94, v78, v172
	v_max3_f32 v128, v95, v79, v128
	v_max_f32_e32 v128, v128, v172
	v_cmp_lt_f32_e32 vcc, s65, v128
	s_cbranch_vccnz .Lgf_rareB
.Lgf_rareB_ret:
	v_exp_f32_e32 v80, v80
	v_exp_f32_e32 v81, v81
	v_exp_f32_e32 v82, v82
	v_add_f32_e32 v182, v80, v182
	v_exp_f32_e32 v83, v83
	v_add_f32_e32 v183, v81, v183
	v_exp_f32_e32 v84, v84
	v_add_f32_e32 v182, v82, v182
	s_waitcnt lgkmcnt(7)
	v_mfma_f32_32x32x16_bf16 v[48:63], v[96:99], v[136:139], 0
	v_exp_f32_e32 v85, v85
	v_add_f32_e32 v183, v83, v183
	v_exp_f32_e32 v86, v86
	v_add_f32_e32 v182, v84, v182
	v_exp_f32_e32 v87, v87
	v_add_f32_e32 v183, v85, v183
	s_waitcnt lgkmcnt(6)
	v_mfma_f32_32x32x16_bf16 v[32:47], v[100:103], v[136:139], 0
	v_cvt_pk_bf16_f32 v80, v80, v81
	v_add_f32_e32 v182, v86, v182
	v_cvt_pk_bf16_f32 v81, v82, v83
	v_add_f32_e32 v183, v87, v183
	v_cvt_pk_bf16_f32 v82, v84, v85
	v_cvt_pk_bf16_f32 v83, v86, v87
	s_waitcnt lgkmcnt(5)
	v_mfma_f32_32x32x16_bf16 v[48:63], v[104:107], v[140:143], v[48:63]
	v_exp_f32_e32 v88, v88
	v_exp_f32_e32 v89, v89
	v_exp_f32_e32 v90, v90
	v_add_f32_e32 v182, v88, v182
	v_exp_f32_e32 v91, v91
	v_add_f32_e32 v183, v89, v183
	s_waitcnt lgkmcnt(4)
	v_mfma_f32_32x32x16_bf16 v[32:47], v[108:111], v[140:143], v[32:47]
	v_exp_f32_e32 v92, v92
	v_add_f32_e32 v182, v90, v182
	v_exp_f32_e32 v93, v93
	v_add_f32_e32 v183, v91, v183
	v_exp_f32_e32 v94, v94
	v_add_f32_e32 v182, v92, v182
	s_waitcnt vmcnt(0)
	s_waitcnt lgkmcnt(0)
	s_barrier
	s_add_i32 s0, s45, 1
	s_cmp_ge_u32 s0, s19
	s_cbranch_scc1 .Lgf_skipKB
	s_add_i32 m0, s46, 0
	s_nop 0
	global_load_lds_dwordx4 v[214:215], off
	global_load_lds_dwordx4 v[216:217], off offset:1024
	v_lshl_add_u64 v[214:215], v[214:215], 0, s[20:21]
	v_lshl_add_u64 v[216:217], v[216:217], 0, s[20:21]
.Lgf_skipKB:
	s_cmp_ge_u32 s45, s19
	s_cbranch_scc1 .Lgf_lastVB
	s_add_i32 m0, s46, 18432
	s_nop 0
	global_load_lds_dwordx4 v[164:165], off
	global_load_lds_dwordx4 v[166:167], off offset:1024
	v_lshl_add_u64 v[164:165], v[164:165], 0, s[84:85]
	v_lshl_add_u64 v[166:167], v[166:167], 0, s[84:85]
	s_branch .Lgf_skipVB

; #define MFMA(a, b, c) __builtin_amdgcn_mfma_f32_32x32x16_bf16((a), (b), (c), 0, 0, 0)
; DI unsigned pack2(float a, float b) { f32x2v f = {a, b}; bf16x2v v = __builtin_convertvector(f, bf16x2v); return __builtin_bit_cast(unsigned, v); }
;   DI void qk(int buf, f32x16 (&s)[2]) {
;     const u16* kb = sK + buf * KBUF + sr * KP + h * 8;
; #pragma unroll
;     for (int kb2 = 0; kb2 < 2; ++kb2)
; #pragma unroll
;       for (int i = 0; i < 16; ++i) s[kb2][i] = 0.f;
; #pragma unroll
;     for (int ks = 0; ks < NKS; ++ks)
; #pragma unroll
;       for (int kb2 = 0; kb2 < 2; ++kb2) {
;         const bf16x8 a = *(const bf16x8*)(kb + kb2 * 32 * KP + ks * 16);
;         s[kb2] = MFMA(a, qf[ks], s[kb2]);
;       }
;     s[0] = MFMA(kone, qm, s[0]);
;     s[1] = MFMA(kone, qm, s[1]);
;   }
;   template <int PAR>
;   DI void step(int t, f32x16 (&cur)[2], f32x16 (&nxt)[2]) {
;     ...
;     const u16* vb = sV + PAR * VBUF + r * GP + h * 8;
; #pragma unroll
;     for (int kb2 = 0; kb2 < 2; ++kb2)
; #pragma unroll
;       for (int s2 = 0; s2 < 2; ++s2) {
;         u32x4 pk = {pack2(cur[kb2][8 * s2], cur[kb2][8 * s2 + 1]), pack2(cur[kb2][8 * s2 + 2], cur[kb2][8 * s2 + 3]),
;                     pack2(cur[kb2][8 * s2 + 4], cur[kb2][8 * s2 + 5]), pack2(cur[kb2][8 * s2 + 6], cur[kb2][8 * s2 + 7])};
;         const bf16x8 pf = __builtin_bit_cast(bf16x8, pk);
; #pragma unroll
;         for (int db = 0; db < 2; ++db) {
;           const bf16x8 a = *(const bf16x8*)(vb + db * 32 * GP + kb2 * 32 + s2 * 16);
;           o[db] = MFMA(a, pf, o[db]);
;         }
;       }
.Lgf_skipVB:
	ds_read_b128 v[96:99], v156 offset:27648
	ds_read_b128 v[100:103], v156 offset:31744
	ds_read_b128 v[104:107], v157 offset:27648
	ds_read_b128 v[108:111], v157 offset:31744
	v_mfma_f32_32x32x16_bf16 v[48:63], v[112:115], v[144:147], v[48:63]
	ds_read_b128 v[112:115], v158 offset:27648
	v_exp_f32_e32 v95, v95
	v_add_f32_e32 v183, v93, v183
	v_cvt_pk_bf16_f32 v88, v88, v89
	v_add_f32_e32 v182, v94, v182
	v_cvt_pk_bf16_f32 v89, v90, v91
	v_add_f32_e32 v183, v95, v183
	v_mfma_f32_32x32x16_bf16 v[32:47], v[116:119], v[144:147], v[32:47]
	ds_read_b128 v[116:119], v158 offset:31744
	v_cvt_pk_bf16_f32 v90, v92, v93
	v_cvt_pk_bf16_f32 v91, v94, v95
	v_exp_f32_e32 v64, v64
	v_exp_f32_e32 v65, v65
	v_exp_f32_e32 v66, v66
	v_add_f32_e32 v182, v64, v182
	v_mfma_f32_32x32x16_bf16 v[48:63], v[120:123], v[148:151], v[48:63]
	ds_read_b128 v[120:123], v159 offset:27648
	v_exp_f32_e32 v67, v67
	v_add_f32_e32 v183, v65, v183
	v_exp_f32_e32 v68, v68
	v_add_f32_e32 v182, v66, v182
	v_exp_f32_e32 v69, v69
	v_add_f32_e32 v183, v67, v183
	v_mfma_f32_32x32x16_bf16 v[32:47], v[124:127], v[148:151], v[32:47]
	ds_read_b128 v[124:127], v159 offset:31744
	v_exp_f32_e32 v70, v70
	v_add_f32_e32 v182, v68, v182
	v_exp_f32_e32 v71, v71
	v_add_f32_e32 v183, v69, v183
	v_cvt_pk_bf16_f32 v64, v64, v65
	v_add_f32_e32 v182, v70, v182
	s_waitcnt lgkmcnt(7)
	v_mfma_f32_32x32x16_bf16 v[16:31], v[96:99], v[80:83], v[16:31]
	ds_read_b128 v[96:99], v152 offset:9216
	v_cvt_pk_bf16_f32 v65, v66, v67
	v_add_f32_e32 v183, v71, v183
	v_cvt_pk_bf16_f32 v66, v68, v69
	v_cvt_pk_bf16_f32 v67, v70, v71
	v_exp_f32_e32 v72, v72
	s_waitcnt lgkmcnt(7)
	v_mfma_f32_32x32x16_bf16 v[0:15], v[100:103], v[80:83], v[0:15]
	ds_read_b128 v[100:103], v152 offset:13312
	v_exp_f32_e32 v73, v73
	v_exp_f32_e32 v74, v74
	v_add_f32_e32 v182, v72, v182
	v_exp_f32_e32 v75, v75
	v_add_f32_e32 v183, v73, v183
	s_waitcnt lgkmcnt(7)
	v_mfma_f32_32x32x16_bf16 v[16:31], v[104:107], v[88:91], v[16:31]
	ds_read_b128 v[104:107], v153 offset:9216
	v_exp_f32_e32 v76, v76
	v_add_f32_e32 v182, v74, v182
	v_exp_f32_e32 v77, v77
	v_add_f32_e32 v183, v75, v183
	v_exp_f32_e32 v78, v78
	s_waitcnt lgkmcnt(7)
	v_mfma_f32_32x32x16_bf16 v[0:15], v[108:111], v[88:91], v[0:15]
	ds_read_b128 v[108:111], v153 offset:13312
	v_add_f32_e32 v182, v76, v182
	v_exp_f32_e32 v79, v79
	v_add_f32_e32 v183, v77, v183
	v_cvt_pk_bf16_f32 v72, v72, v73
	v_add_f32_e32 v182, v78, v182
	s_waitcnt lgkmcnt(7)
	v_mfma_f32_32x32x16_bf16 v[16:31], v[112:115], v[64:67], v[16:31]
	ds_read_b128 v[112:115], v154 offset:9216
	v_cvt_pk_bf16_f32 v73, v74, v75
	v_add_f32_e32 v183, v79, v183
	v_cvt_pk_bf16_f32 v74, v76, v77
	v_cvt_pk_bf16_f32 v75, v78, v79
	v_max3_f32 v128, v48, v32, v49
	s_waitcnt lgkmcnt(7)
	v_mfma_f32_32x32x16_bf16 v[0:15], v[116:119], v[64:67], v[0:15]
	ds_read_b128 v[116:119], v154 offset:13312
	v_max3_f32 v172, v33, v50, v34
	v_max3_f32 v128, v51, v35, v128
	v_max3_f32 v172, v52, v36, v172
	v_max3_f32 v128, v53, v37, v128
	v_max3_f32 v172, v54, v38, v172
	s_waitcnt lgkmcnt(7)
	v_mfma_f32_32x32x16_bf16 v[16:31], v[120:123], v[72:75], v[16:31]
	ds_read_b128 v[120:123], v155 offset:9216
	v_max3_f32 v128, v55, v39, v128
	v_max3_f32 v172, v56, v40, v172
	v_max3_f32 v128, v57, v41, v128
	v_max3_f32 v172, v58, v42, v172
	v_max3_f32 v128, v59, v43, v128
	s_waitcnt lgkmcnt(7)
	v_mfma_f32_32x32x16_bf16 v[0:15], v[124:127], v[72:75], v[0:15]
	ds_read_b128 v[124:127], v155 offset:13312
	v_max3_f32 v172, v60, v44, v172
	v_max3_f32 v128, v61, v45, v128
	v_max3_f32 v172, v62, v46, v172
	v_max3_f32 v128, v63, v47, v128
	v_max_f32_e32 v128, v128, v172
	v_lshl_add_u64 v[130:131], v[130:131], 0, s[84:85]
	v_lshl_add_u64 v[180:181], v[180:181], 0, s[84:85]
	s_mov_b32 s0, s45
	s_add_i32 s45, s45, 2
	s_cmp_lt_u32 s0, s19
	s_cbranch_scc1 .Lgf_top
	s_branch .Lg_fold

; DI unsigned pack2(float a, float b) { f32x2v f = {a, b}; bf16x2v v = __builtin_convertvector(f, bf16x2v); return __builtin_bit_cast(unsigned, v); }
; DI float xhalf(float v) { return __shfl_xor(v, 32); }
;   template <int PAR>
;   DI void step(int t, f32x16 (&cur)[2], f32x16 (&nxt)[2]) {
;     if (t + 1 < nt) sstore_k(PAR ^ 1);
;     if (t > 0) sstore_v(PAR);
;     __syncthreads();
;     if (t + 1 < nt) qk(PAR ^ 1, nxt);
;     float mx = fmaxf(cur[0][0], cur[1][0]);
; #pragma unroll
;     for (int i = 1; i < 16; ++i) mx = fmaxf(fmaxf(cur[0][i], cur[1][i]), mx);
;     if (__builtin_amdgcn_ballot_w64(mx > ATT_THR) != 0ull) {
;       asm volatile("" ::: "memory");
;       mx = fmaxf(mx, xhalf(mx));
;       const float want = mref + fmaxf(mx, 0.f);
;       const float mn = __uint_as_float(pack2(want, 0.f) << 16);
;       const float d = mn - mref;
;       const float alpha = __builtin_amdgcn_exp2f(-d);
;       mref = mn;
;       l *= alpha;
; #pragma unroll
;       for (int a = 0; a < 2; ++a)
; #pragma unroll
;         for (int i = 0; i < 16; ++i) { o[a][i] *= alpha; cur[a][i] -= d; nxt[a][i] -= d; }
;       u32x4 q4 = {h == 0 ? (pack2(-mn, 0.f) & 0xffffu) : 0u, 0u, 0u, 0u};
;       qm = __builtin_bit_cast(bf16x8, q4);
;     }
;     float psum = 0.f;
; #pragma unroll
;     for (int kb2 = 0; kb2 < 2; ++kb2)
; #pragma unroll
;       for (int i = 0; i < 16; ++i) { const float pv = __builtin_amdgcn_exp2f(cur[kb2][i]); cur[kb2][i] = pv; psum += pv; }
;     l += psum;
;     if (t + 2 < nt) gload_k(t + 2);
;     if (t + 1 < nt) gload_v(t + 1);
.Lg_rareA_ret:
	v_exp_f32_e32 v48, v48
	v_exp_f32_e32 v49, v49
	v_exp_f32_e32 v50, v50
	v_add_f32_e32 v182, v48, v182
	v_exp_f32_e32 v51, v51
	v_add_f32_e32 v183, v49, v183
	v_exp_f32_e32 v52, v52
	v_add_f32_e32 v182, v50, v182
	s_waitcnt lgkmcnt(7)
	v_mfma_f32_32x32x16_bf16 v[80:95], v[96:99], v[136:139], 0
	v_exp_f32_e32 v53, v53
	v_add_f32_e32 v183, v51, v183
	v_exp_f32_e32 v54, v54
	v_add_f32_e32 v182, v52, v182
	v_exp_f32_e32 v55, v55
	s_waitcnt lgkmcnt(6)
	v_mfma_f32_32x32x16_bf16 v[64:79], v[100:103], v[136:139], 0
	v_add_f32_e32 v183, v53, v183
	v_cvt_pk_bf16_f32 v48, v48, v49
	v_add_f32_e32 v182, v54, v182
	v_cvt_pk_bf16_f32 v49, v50, v51
	v_add_f32_e32 v183, v55, v183
	s_waitcnt lgkmcnt(5)
	v_mfma_f32_32x32x16_bf16 v[80:95], v[104:107], v[140:143], v[80:95]
	v_cvt_pk_bf16_f32 v50, v52, v53
	v_cvt_pk_bf16_f32 v51, v54, v55
	v_exp_f32_e32 v56, v56
	v_exp_f32_e32 v57, v57
	v_exp_f32_e32 v58, v58
	s_waitcnt lgkmcnt(4)
	v_mfma_f32_32x32x16_bf16 v[64:79], v[108:111], v[140:143], v[64:79]
	v_add_f32_e32 v182, v56, v182
	v_exp_f32_e32 v59, v59
	v_add_f32_e32 v183, v57, v183
	v_exp_f32_e32 v60, v60
	v_add_f32_e32 v182, v58, v182
	s_waitcnt vmcnt(0)
	s_waitcnt lgkmcnt(0)
	s_barrier
	s_add_i32 s0, s45, -1
	s_cmp_ge_u32 s0, s19
	s_cselect_b64 s[14:15], -1, 0
	s_cmp_ge_u32 s45, s19
	s_cbranch_scc1 .Lg_skipKA
	s_add_i32 m0, s46, 9216
	s_nop 0
	global_load_lds_dwordx4 v[214:215], off
	global_load_lds_dwordx4 v[216:217], off offset:1024
	v_lshl_add_u64 v[214:215], v[214:215], 0, s[20:21]
	v_lshl_add_u64 v[216:217], v[216:217], 0, s[20:21]
;   DI void qk(int buf, f32x16 (&s)[2]) {
;     const u16* kb = sK + buf * KBUF + sr * KP + h * 8;
; #pragma unroll
;     for (int kb2 = 0; kb2 < 2; ++kb2)
; #pragma unroll
;       for (int i = 0; i < 16; ++i) s[kb2][i] = 0.f;
; #pragma unroll
;     for (int ks = 0; ks < NKS; ++ks)
; #pragma unroll
;       for (int kb2 = 0; kb2 < 2; ++kb2) {
;         const bf16x8 a = *(const bf16x8*)(kb + kb2 * 32 * KP + ks * 16);
;         s[kb2] = MFMA(a, qf[ks], s[kb2]);
;       }
;     s[0] = MFMA(kone, qm, s[0]);
;     s[1] = MFMA(kone, qm, s[1]);
;   }
;   template <int PAR>
;   DI void step(int t, f32x16 (&cur)[2], f32x16 (&nxt)[2]) {
;     if (t + 1 < nt) sstore_k(PAR ^ 1);
;     if (t > 0) sstore_v(PAR);
;     __syncthreads();
;     if (t + 1 < nt) qk(PAR ^ 1, nxt);
;     float mx = fmaxf(cur[0][0], cur[1][0]);
; #pragma unroll
;     for (int i = 1; i < 16; ++i) mx = fmaxf(fmaxf(cur[0][i], cur[1][i]), mx);
;     if (__builtin_amdgcn_ballot_w64(mx > ATT_THR) != 0ull) {
;       asm volatile("" ::: "memory");
;       mx = fmaxf(mx, xhalf(mx));
;       const float want = mref + fmaxf(mx, 0.f);
;       const float mn = __uint_as_float(pack2(want, 0.f) << 16);
;       const float d = mn - mref;
;       const float alpha = __builtin_amdgcn_exp2f(-d);
;       mref = mn;
;       l *= alpha;
; #pragma unroll
;       for (int a = 0; a < 2; ++a)
; #pragma unroll
;         for (int i = 0; i < 16; ++i) { o[a][i] *= alpha; cur[a][i] -= d; nxt[a][i] -= d; }
;       u32x4 q4 = {h == 0 ? (pack2(-mn, 0.f) & 0xffffu) : 0u, 0u, 0u, 0u};
;       qm = __builtin_bit_cast(bf16x8, q4);
;     }
;     float psum = 0.f;
; #pragma unroll
;     for (int kb2 = 0; kb2 < 2; ++kb2)
; #pragma unroll
;       for (int i = 0; i < 16; ++i) { const float pv = __builtin_amdgcn_exp2f(cur[kb2][i]); cur[kb2][i] = pv; psum += pv; }
;     l += psum;
;     if (t + 2 < nt) gload_k(t + 2);
;     if (t + 1 < nt) gload_v(t + 1);
;     const u16* vb = sV + PAR * VBUF + r * GP + h * 8;
; #pragma unroll
;     for (int kb2 = 0; kb2 < 2; ++kb2)
; #pragma unroll
;       for (int s2 = 0; s2 < 2; ++s2) {
;         u32x4 pk = {pack2(cur[kb2][8 * s2], cur[kb2][8 * s2 + 1]), pack2(cur[kb2][8 * s2 + 2], cur[kb2][8 * s2 + 3]),
;                     pack2(cur[kb2][8 * s2 + 4], cur[kb2][8 * s2 + 5]), pack2(cur[kb2][8 * s2 + 6], cur[kb2][8 * s2 + 7])};
;         const bf16x8 pf = __builtin_bit_cast(bf16x8, pk);
; #pragma unroll
.Lg_skipKA:
	s_add_i32 m0, s46, 27648
	s_nop 0
	global_load_lds_dwordx4 v[160:161], off
	global_load_lds_dwordx4 v[162:163], off offset:1024
	v_lshl_add_u64 v[160:161], v[160:161], 0, s[84:85]
	v_lshl_add_u64 v[162:163], v[162:163], 0, s[84:85]
	ds_read_b128 v[96:99], v156 offset:18432
	ds_read_b128 v[100:103], v156 offset:22528
	ds_read_b128 v[104:107], v157 offset:18432
	ds_read_b128 v[108:111], v157 offset:22528
	v_mfma_f32_32x32x16_bf16 v[80:95], v[112:115], v[144:147], v[80:95]
	ds_read_b128 v[112:115], v158 offset:18432
	v_exp_f32_e32 v61, v61
	v_add_f32_e32 v183, v59, v183
	v_exp_f32_e32 v62, v62
	v_add_f32_e32 v182, v60, v182
	v_exp_f32_e32 v63, v63
	v_mfma_f32_32x32x16_bf16 v[64:79], v[116:119], v[144:147], v[64:79]
	ds_read_b128 v[116:119], v158 offset:22528
	v_add_f32_e32 v183, v61, v183
	v_cvt_pk_bf16_f32 v56, v56, v57
	v_add_f32_e32 v182, v62, v182
	v_cvt_pk_bf16_f32 v57, v58, v59
	v_add_f32_e32 v183, v63, v183
	v_mfma_f32_32x32x16_bf16 v[80:95], v[120:123], v[148:151], v[80:95]
	ds_read_b128 v[120:123], v159 offset:18432
	v_cvt_pk_bf16_f32 v58, v60, v61
	v_cvt_pk_bf16_f32 v59, v62, v63
	v_exp_f32_e32 v32, v32
	v_exp_f32_e32 v33, v33
	v_exp_f32_e32 v34, v34
	v_mfma_f32_32x32x16_bf16 v[64:79], v[124:127], v[148:151], v[64:79]
	ds_read_b128 v[124:127], v159 offset:22528
	v_add_f32_e32 v182, v32, v182
	v_exp_f32_e32 v35, v35
	v_add_f32_e32 v183, v33, v183
	v_exp_f32_e32 v36, v36
	v_add_f32_e32 v182, v34, v182
	v_mfma_f32_32x32x16_bf16 v[80:95], v[132:135], v[168:171], v[80:95]
	v_exp_f32_e32 v37, v37
	v_add_f32_e32 v183, v35, v183
	v_exp_f32_e32 v38, v38
	v_add_f32_e32 v182, v36, v182
	v_exp_f32_e32 v39, v39
	v_mfma_f32_32x32x16_bf16 v[64:79], v[132:135], v[168:171], v[64:79]
	v_add_f32_e32 v183, v37, v183
	v_cvt_pk_bf16_f32 v32, v32, v33
	v_add_f32_e32 v182, v38, v182
	v_cvt_pk_bf16_f32 v33, v34, v35
	v_add_f32_e32 v183, v39, v183
	s_waitcnt lgkmcnt(7)
	v_mfma_f32_32x32x16_bf16 v[16:31], v[96:99], v[48:51], v[16:31]
	ds_read_b128 v[96:99], v152
	v_cvt_pk_bf16_f32 v34, v36, v37
	v_cvt_pk_bf16_f32 v35, v38, v39
	v_exp_f32_e32 v40, v40
	v_exp_f32_e32 v41, v41
	v_exp_f32_e32 v42, v42
	s_waitcnt lgkmcnt(7)
	v_mfma_f32_32x32x16_bf16 v[0:15], v[100:103], v[48:51], v[0:15]
	ds_read_b128 v[100:103], v152 offset:4096
	v_add_f32_e32 v182, v40, v182
	v_exp_f32_e32 v43, v43
	v_add_f32_e32 v183, v41, v183
	v_exp_f32_e32 v44, v44
	v_add_f32_e32 v182, v42, v182
	s_waitcnt lgkmcnt(7)
	v_mfma_f32_32x32x16_bf16 v[16:31], v[104:107], v[56:59], v[16:31]
	ds_read_b128 v[104:107], v153
	v_exp_f32_e32 v45, v45
	v_add_f32_e32 v183, v43, v183
	v_exp_f32_e32 v46, v46
	v_add_f32_e32 v182, v44, v182
	v_exp_f32_e32 v47, v47
	s_waitcnt lgkmcnt(7)
	v_mfma_f32_32x32x16_bf16 v[0:15], v[108:111], v[56:59], v[0:15]
	ds_read_b128 v[108:111], v153 offset:4096
	v_add_f32_e32 v183, v45, v183
	v_cvt_pk_bf16_f32 v40, v40, v41
	v_add_f32_e32 v182, v46, v182
	v_cvt_pk_bf16_f32 v41, v42, v43
	v_add_f32_e32 v183, v47, v183
	s_waitcnt lgkmcnt(7)
	v_mfma_f32_32x32x16_bf16 v[16:31], v[112:115], v[32:35], v[16:31]
	ds_read_b128 v[112:115], v154
	v_cvt_pk_bf16_f32 v42, v44, v45
	v_cvt_pk_bf16_f32 v43, v46, v47
	v_max3_f32 v128, v80, v64, v81
	v_max3_f32 v172, v65, v82, v66
	v_max3_f32 v128, v83, v67, v128
	s_waitcnt lgkmcnt(7)
	v_mfma_f32_32x32x16_bf16 v[0:15], v[116:119], v[32:35], v[0:15]
	ds_read_b128 v[116:119], v154 offset:4096
	v_max3_f32 v172, v84, v68, v172
	v_max3_f32 v128, v85, v69, v128
	v_max3_f32 v172, v86, v70, v172
	v_max3_f32 v128, v87, v71, v128
	v_max3_f32 v172, v88, v72, v172
	s_waitcnt lgkmcnt(7)
	v_mfma_f32_32x32x16_bf16 v[16:31], v[120:123], v[40:43], v[16:31]
	ds_read_b128 v[120:123], v155
	v_max3_f32 v128, v89, v73, v128
	v_max3_f32 v172, v90, v74, v172
	v_max3_f32 v128, v91, v75, v128
	v_max3_f32 v172, v92, v76, v172
	s_waitcnt lgkmcnt(7)
	v_mfma_f32_32x32x16_bf16 v[0:15], v[124:127], v[40:43], v[0:15]
	ds_read_b128 v[124:127], v155 offset:4096
	v_max3_f32 v128, v93, v77, v128
	v_max3_f32 v172, v94, v78, v172
	v_max3_f32 v128, v95, v79, v128
	v_max_f32_e32 v128, v128, v172
	v_cmp_lt_f32_e32 vcc, s65, v128
	s_cbranch_vccnz .Lg_rareB
.Lg_rareB_ret:
	v_exp_f32_e32 v80, v80
	v_exp_f32_e32 v81, v81
	v_exp_f32_e32 v82, v82
	v_add_f32_e32 v182, v80, v182
	v_exp_f32_e32 v83, v83
	v_add_f32_e32 v183, v81, v183
	v_exp_f32_e32 v84, v84
	v_add_f32_e32 v182, v82, v182
	s_waitcnt lgkmcnt(7)
	v_mfma_f32_32x32x16_bf16 v[48:63], v[96:99], v[136:139], 0
	v_exp_f32_e32 v85, v85
	v_add_f32_e32 v183, v83, v183
	v_exp_f32_e32 v86, v86
	v_add_f32_e32 v182, v84, v182
	v_exp_f32_e32 v87, v87
	s_waitcnt lgkmcnt(6)
	v_mfma_f32_32x32x16_bf16 v[32:47], v[100:103], v[136:139], 0
	v_add_f32_e32 v183, v85, v183
	v_cvt_pk_bf16_f32 v80, v80, v81
	v_add_f32_e32 v182, v86, v182
	v_cvt_pk_bf16_f32 v81, v82, v83
	v_add_f32_e32 v183, v87, v183
	s_waitcnt lgkmcnt(5)
	v_mfma_f32_32x32x16_bf16 v[48:63], v[104:107], v[140:143], v[48:63]
	v_cvt_pk_bf16_f32 v82, v84, v85
	v_cvt_pk_bf16_f32 v83, v86, v87
	v_exp_f32_e32 v88, v88
	v_exp_f32_e32 v89, v89
	v_exp_f32_e32 v90, v90
	s_waitcnt lgkmcnt(4)
	v_mfma_f32_32x32x16_bf16 v[32:47], v[108:111], v[140:143], v[32:47]
	v_add_f32_e32 v182, v88, v182
	v_exp_f32_e32 v91, v91
	v_add_f32_e32 v183, v89, v183
	v_exp_f32_e32 v92, v92
	v_add_f32_e32 v182, v90, v182
	s_waitcnt vmcnt(0)
	s_waitcnt lgkmcnt(0)
	s_barrier
	s_add_i32 s0, s45, 1
	s_cmp_ge_u32 s0, s19
	s_cbranch_scc1 .Lg_skipKB
	s_add_i32 m0, s46, 0
	s_nop 0
	global_load_lds_dwordx4 v[214:215], off
	global_load_lds_dwordx4 v[216:217], off offset:1024
	v_lshl_add_u64 v[214:215], v[214:215], 0, s[20:21]
	v_lshl_add_u64 v[216:217], v[216:217], 0, s[20:21]

; #define MFMA(a, b, c) __builtin_amdgcn_mfma_f32_32x32x16_bf16((a), (b), (c), 0, 0, 0)
; DI unsigned pack2(float a, float b) { f32x2v f = {a, b}; bf16x2v v = __builtin_convertvector(f, bf16x2v); return __builtin_bit_cast(unsigned, v); }
;   DI void qk(int buf, f32x16 (&s)[2]) {
;     const u16* kb = sK + buf * KBUF + sr * KP + h * 8;
; #pragma unroll
;     for (int kb2 = 0; kb2 < 2; ++kb2)
; #pragma unroll
;       for (int i = 0; i < 16; ++i) s[kb2][i] = 0.f;
; #pragma unroll
;     for (int ks = 0; ks < NKS; ++ks)
; #pragma unroll
;       for (int kb2 = 0; kb2 < 2; ++kb2) {
;         const bf16x8 a = *(const bf16x8*)(kb + kb2 * 32 * KP + ks * 16);
;         s[kb2] = MFMA(a, qf[ks], s[kb2]);
;       }
;     s[0] = MFMA(kone, qm, s[0]);
;     s[1] = MFMA(kone, qm, s[1]);
;   }
;   template <int PAR>
;   DI void step(int t, f32x16 (&cur)[2], f32x16 (&nxt)[2]) {
;     ...
;     const u16* vb = sV + PAR * VBUF + r * GP + h * 8;
; #pragma unroll
;     for (int kb2 = 0; kb2 < 2; ++kb2)
; #pragma unroll
;       for (int s2 = 0; s2 < 2; ++s2) {
;         u32x4 pk = {pack2(cur[kb2][8 * s2], cur[kb2][8 * s2 + 1]), pack2(cur[kb2][8 * s2 + 2], cur[kb2][8 * s2 + 3]),
;                     pack2(cur[kb2][8 * s2 + 4], cur[kb2][8 * s2 + 5]), pack2(cur[kb2][8 * s2 + 6], cur[kb2][8 * s2 + 7])};
;         const bf16x8 pf = __builtin_bit_cast(bf16x8, pk);
; #pragma unroll
;         for (int db = 0; db < 2; ++db) {
;           const bf16x8 a = *(const bf16x8*)(vb + db * 32 * GP + kb2 * 32 + s2 * 16);
;           o[db] = MFMA(a, pf, o[db]);
;         }
;       }
.Lg_skipVB:
	ds_read_b128 v[96:99], v156 offset:27648
	ds_read_b128 v[100:103], v156 offset:31744
	ds_read_b128 v[104:107], v157 offset:27648
	ds_read_b128 v[108:111], v157 offset:31744
	v_mfma_f32_32x32x16_bf16 v[48:63], v[112:115], v[144:147], v[48:63]
	ds_read_b128 v[112:115], v158 offset:27648
	v_exp_f32_e32 v93, v93
	v_add_f32_e32 v183, v91, v183
	v_exp_f32_e32 v94, v94
	v_add_f32_e32 v182, v92, v182
	v_exp_f32_e32 v95, v95
	v_mfma_f32_32x32x16_bf16 v[32:47], v[116:119], v[144:147], v[32:47]
	ds_read_b128 v[116:119], v158 offset:31744
	v_add_f32_e32 v183, v93, v183
	v_cvt_pk_bf16_f32 v88, v88, v89
	v_add_f32_e32 v182, v94, v182
	v_cvt_pk_bf16_f32 v89, v90, v91
	v_add_f32_e32 v183, v95, v183
	v_mfma_f32_32x32x16_bf16 v[48:63], v[120:123], v[148:151], v[48:63]
	ds_read_b128 v[120:123], v159 offset:27648
	v_cvt_pk_bf16_f32 v90, v92, v93
	v_cvt_pk_bf16_f32 v91, v94, v95
	v_exp_f32_e32 v64, v64
	v_exp_f32_e32 v65, v65
	v_exp_f32_e32 v66, v66
	v_mfma_f32_32x32x16_bf16 v[32:47], v[124:127], v[148:151], v[32:47]
	ds_read_b128 v[124:127], v159 offset:31744
	v_add_f32_e32 v182, v64, v182
	v_exp_f32_e32 v67, v67
	v_add_f32_e32 v183, v65, v183
	v_exp_f32_e32 v68, v68
	v_add_f32_e32 v182, v66, v182
	v_mfma_f32_32x32x16_bf16 v[48:63], v[132:135], v[168:171], v[48:63]
	v_exp_f32_e32 v69, v69
	v_add_f32_e32 v183, v67, v183
	v_exp_f32_e32 v70, v70
	v_add_f32_e32 v182, v68, v182
	v_exp_f32_e32 v71, v71
	v_mfma_f32_32x32x16_bf16 v[32:47], v[132:135], v[168:171], v[32:47]
	v_add_f32_e32 v183, v69, v183
	v_cvt_pk_bf16_f32 v64, v64, v65
	v_add_f32_e32 v182, v70, v182
	v_cvt_pk_bf16_f32 v65, v66, v67
	v_add_f32_e32 v183, v71, v183
	s_waitcnt lgkmcnt(7)
	v_mfma_f32_32x32x16_bf16 v[16:31], v[96:99], v[80:83], v[16:31]
	ds_read_b128 v[96:99], v152 offset:9216
	v_cvt_pk_bf16_f32 v66, v68, v69
	v_cvt_pk_bf16_f32 v67, v70, v71
	v_exp_f32_e32 v72, v72
	v_exp_f32_e32 v73, v73
	v_exp_f32_e32 v74, v74
	s_waitcnt lgkmcnt(7)
	v_mfma_f32_32x32x16_bf16 v[0:15], v[100:103], v[80:83], v[0:15]
	ds_read_b128 v[100:103], v152 offset:13312
	v_add_f32_e32 v182, v72, v182
	v_exp_f32_e32 v75, v75
	v_add_f32_e32 v183, v73, v183
	v_exp_f32_e32 v76, v76
	v_add_f32_e32 v182, v74, v182
	s_waitcnt lgkmcnt(7)
	v_mfma_f32_32x32x16_bf16 v[16:31], v[104:107], v[88:91], v[16:31]
	ds_read_b128 v[104:107], v153 offset:9216
	v_exp_f32_e32 v77, v77
	v_add_f32_e32 v183, v75, v183
	v_exp_f32_e32 v78, v78
	v_add_f32_e32 v182, v76, v182
	v_exp_f32_e32 v79, v79
	s_waitcnt lgkmcnt(7)
	v_mfma_f32_32x32x16_bf16 v[0:15], v[108:111], v[88:91], v[0:15]
	ds_read_b128 v[108:111], v153 offset:13312
	v_add_f32_e32 v183, v77, v183
	v_cvt_pk_bf16_f32 v72, v72, v73
	v_add_f32_e32 v182, v78, v182
	v_cvt_pk_bf16_f32 v73, v74, v75
	v_add_f32_e32 v183, v79, v183
	s_waitcnt lgkmcnt(7)
	v_mfma_f32_32x32x16_bf16 v[16:31], v[112:115], v[64:67], v[16:31]
	ds_read_b128 v[112:115], v154 offset:9216
	v_cvt_pk_bf16_f32 v74, v76, v77
	v_cvt_pk_bf16_f32 v75, v78, v79
	v_max3_f32 v128, v48, v32, v49
	v_max3_f32 v172, v33, v50, v34
	v_max3_f32 v128, v51, v35, v128
	s_waitcnt lgkmcnt(7)
	v_mfma_f32_32x32x16_bf16 v[0:15], v[116:119], v[64:67], v[0:15]
	ds_read_b128 v[116:119], v154 offset:13312
	v_max3_f32 v172, v52, v36, v172
	v_max3_f32 v128, v53, v37, v128
	v_max3_f32 v172, v54, v38, v172
	v_max3_f32 v128, v55, v39, v128
	v_max3_f32 v172, v56, v40, v172
	s_waitcnt lgkmcnt(7)
	v_mfma_f32_32x32x16_bf16 v[16:31], v[120:123], v[72:75], v[16:31]
	ds_read_b128 v[120:123], v155 offset:9216
	v_max3_f32 v128, v57, v41, v128
	v_max3_f32 v172, v58, v42, v172
	v_max3_f32 v128, v59, v43, v128
	v_max3_f32 v172, v60, v44, v172
	s_waitcnt lgkmcnt(7)
	v_mfma_f32_32x32x16_bf16 v[0:15], v[124:127], v[72:75], v[0:15]
	ds_read_b128 v[124:127], v155 offset:13312
	v_max3_f32 v128, v61, v45, v128
	v_max3_f32 v172, v62, v46, v172
	v_max3_f32 v128, v63, v47, v128
	v_max_f32_e32 v128, v128, v172
	v_lshl_add_u64 v[130:131], v[130:131], 0, s[84:85]
	v_lshl_add_u64 v[180:181], v[180:181], 0, s[84:85]
	s_mov_b32 s0, s45
	s_add_i32 s45, s45, 2
	s_cmp_lt_u32 s0, s19
	s_cbranch_scc1 .LBB0_238
	s_branch .Lg_fold

; DI unsigned pack2(float a, float b) { f32x2v f = {a, b}; bf16x2v v = __builtin_convertvector(f, bf16x2v); return __builtin_bit_cast(unsigned, v); }
; DI float xhalf(float v) { return __shfl_xor(v, 32); }
;   template <int PAR>
;   DI void step(int t, f32x16 (&cur)[2], f32x16 (&nxt)[2]) {
;     if (t + 1 < nt) sstore_k(PAR ^ 1);
;     if (t > 0) sstore_v(PAR);
;     __syncthreads();
;     if (t + 1 < nt) qk(PAR ^ 1, nxt);
;     float mx = fmaxf(cur[0][0], cur[1][0]);
; #pragma unroll
;     for (int i = 1; i < 16; ++i) mx = fmaxf(fmaxf(cur[0][i], cur[1][i]), mx);
;     if (__builtin_amdgcn_ballot_w64(mx > ATT_THR) != 0ull) {
;       asm volatile("" ::: "memory");
;       mx = fmaxf(mx, xhalf(mx));
;       const float want = mref + fmaxf(mx, 0.f);
;       const float mn = __uint_as_float(pack2(want, 0.f) << 16);
;       const float d = mn - mref;
;       const float alpha = __builtin_amdgcn_exp2f(-d);
;       mref = mn;
;       l *= alpha;
; #pragma unroll
;       for (int a = 0; a < 2; ++a)
; #pragma unroll
;         for (int i = 0; i < 16; ++i) { o[a][i] *= alpha; cur[a][i] -= d; nxt[a][i] -= d; }
;       u32x4 q4 = {h == 0 ? (pack2(-mn, 0.f) & 0xffffu) : 0u, 0u, 0u, 0u};
;       qm = __builtin_bit_cast(bf16x8, q4);
;     }
;     float psum = 0.f;
; #pragma unroll
;     for (int kb2 = 0; kb2 < 2; ++kb2)
; #pragma unroll
;       for (int i = 0; i < 16; ++i) { const float pv = __builtin_amdgcn_exp2f(cur[kb2][i]); cur[kb2][i] = pv; psum += pv; }
;     l += psum;
;     if (t + 2 < nt) gload_k(t + 2);
;     if (t + 1 < nt) gload_v(t + 1);
.Lmf_top:
	v_cmp_lt_f32_e32 vcc, s65, v240
	s_cbranch_vccnz .Lmf_rareA
.Lmf_rareA_ret:
	s_waitcnt vmcnt(0)
	ds_write_b128 v250, v[160:163]
	ds_write_b128 v251, v[164:167]
	ds_write_b128 v252, v[168:171]
	ds_write_b128 v194, v[172:175] offset:26624
	ds_write_b128 v196, v[176:179] offset:26624
	s_add_i32 s0, s31, -1
	s_cmp_ge_u32 s0, s19
	s_cselect_b64 s[14:15], -1, 0
	s_cmp_ge_u32 s31, s19
	s_cbranch_scc1 .Lmf_skipKA
	v_mov_b32_e32 v160, s21
	v_mov_b32_e32 v161, s45
	v_mov_b32_e32 v162, s20
	v_mov_b32_e32 v163, s44
	v_cndmask_b32_e64 v169, v160, v161, s[12:13]
	v_cndmask_b32_e64 v168, v162, v163, s[12:13]
	v_lshl_add_u64 v[168:169], v[204:205], 1, v[168:169]
	v_cndmask_b32_e64 v165, v160, v161, s[10:11]
	v_cndmask_b32_e64 v164, v162, v163, s[10:11]
	v_lshl_add_u64 v[164:165], v[202:203], 1, v[164:165]
	v_cndmask_b32_e64 v167, v160, v161, s[8:9]
	v_cndmask_b32_e64 v166, v162, v163, s[8:9]
	v_lshl_add_u64 v[166:167], v[200:201], 1, v[166:167]
	global_load_dwordx4 v[168:171], v[168:169], off
	global_load_dwordx4 v[160:163], v[166:167], off
	global_load_dwordx4 v[164:167], v[164:165], off
	s_add_u32 s20, s20, 0x10000
	s_addc_u32 s21, s21, 0
	s_add_u32 s44, s44, 0x1000
	s_addc_u32 s45, s45, 0
; #define MFMA(a, b, c) __builtin_amdgcn_mfma_f32_32x32x16_bf16((a), (b), (c), 0, 0, 0)
; DI unsigned pack2(float a, float b) { f32x2v f = {a, b}; bf16x2v v = __builtin_convertvector(f, bf16x2v); return __builtin_bit_cast(unsigned, v); }
; DI float xhalf(float v) { return __shfl_xor(v, 32); }
;   template <int PAR>
;   DI void step(int t, f32x16 (&cur)[2], f32x16 (&nxt)[2]) {
;     if (t + 1 < nt) sstore_k(PAR ^ 1);
;     if (t > 0) sstore_v(PAR);
;     __syncthreads();
;     if (t + 1 < nt) qk(PAR ^ 1, nxt);
;     float mx = fmaxf(cur[0][0], cur[1][0]);
; #pragma unroll
;     for (int i = 1; i < 16; ++i) mx = fmaxf(fmaxf(cur[0][i], cur[1][i]), mx);
;     if (__builtin_amdgcn_ballot_w64(mx > ATT_THR) != 0ull) {
;       asm volatile("" ::: "memory");
;       mx = fmaxf(mx, xhalf(mx));
;       const float want = mref + fmaxf(mx, 0.f);
;       const float mn = __uint_as_float(pack2(want, 0.f) << 16);
;       const float d = mn - mref;
;       const float alpha = __builtin_amdgcn_exp2f(-d);
;       mref = mn;
;       l *= alpha;
; #pragma unroll
;       for (int a = 0; a < 2; ++a)
; #pragma unroll
;         for (int i = 0; i < 16; ++i) { o[a][i] *= alpha; cur[a][i] -= d; nxt[a][i] -= d; }
;       u32x4 q4 = {h == 0 ? (pack2(-mn, 0.f) & 0xffffu) : 0u, 0u, 0u, 0u};
;       qm = __builtin_bit_cast(bf16x8, q4);
;     }
;     float psum = 0.f;
; #pragma unroll
;     for (int kb2 = 0; kb2 < 2; ++kb2)
; #pragma unroll
;       for (int i = 0; i < 16; ++i) { const float pv = __builtin_amdgcn_exp2f(cur[kb2][i]); cur[kb2][i] = pv; psum += pv; }
;     l += psum;
;     if (t + 2 < nt) gload_k(t + 2);
;     if (t + 1 < nt) gload_v(t + 1);
;     const u16* vb = sV + PAR * VBUF + r * GP + h * 8;
; #pragma unroll
;     for (int kb2 = 0; kb2 < 2; ++kb2)
; #pragma unroll
;       for (int s2 = 0; s2 < 2; ++s2) {
;         u32x4 pk = {pack2(cur[kb2][8 * s2], cur[kb2][8 * s2 + 1]), pack2(cur[kb2][8 * s2 + 2], cur[kb2][8 * s2 + 3]),
;                     pack2(cur[kb2][8 * s2 + 4], cur[kb2][8 * s2 + 5]), pack2(cur[kb2][8 * s2 + 6], cur[kb2][8 * s2 + 7])};
;         const bf16x8 pf = __builtin_bit_cast(bf16x8, pk);
; #pragma unroll
;         for (int db = 0; db < 2; ++db) {
;           const bf16x8 a = *(const bf16x8*)(vb + db * 32 * GP + kb2 * 32 + s2 * 16);
;           o[db] = MFMA(a, pf, o[db]);
;         }
;       }
.Lmf_skipKA:
	global_load_dwordx4 v[172:175], v[130:131], off offset:-128
	global_load_dwordx4 v[176:179], v[220:221], off offset:-128
	v_exp_f32_e32 v48, v48
	v_exp_f32_e32 v49, v49
	v_exp_f32_e32 v50, v50
	v_add_f32_e32 v238, v48, v238
	v_exp_f32_e32 v51, v51
	v_add_f32_e32 v239, v49, v239
	v_exp_f32_e32 v52, v52
	v_add_f32_e32 v238, v50, v238
	s_waitcnt lgkmcnt(8)
	v_mfma_f32_32x32x16_bf16 v[80:95], v[96:99], v[136:139], 0
	ds_read_b128 v[96:99], v236 offset:13440
	v_exp_f32_e32 v53, v53
	v_add_f32_e32 v239, v51, v239
	v_exp_f32_e32 v54, v54
	v_add_f32_e32 v238, v52, v238
	v_exp_f32_e32 v55, v55
	s_waitcnt lgkmcnt(8)
	v_mfma_f32_32x32x16_bf16 v[64:79], v[100:103], v[136:139], 0
	ds_read_b128 v[100:103], v236 offset:20096
	v_add_f32_e32 v239, v53, v239
	v_cvt_pk_bf16_f32 v48, v48, v49
	v_add_f32_e32 v238, v54, v238
	v_cvt_pk_bf16_f32 v49, v50, v51
	v_add_f32_e32 v239, v55, v239
	s_waitcnt lgkmcnt(8)
	v_mfma_f32_32x32x16_bf16 v[80:95], v[104:107], v[140:143], v[80:95]
	ds_read_b128 v[104:107], v236 offset:13472
	v_cvt_pk_bf16_f32 v50, v52, v53
	v_cvt_pk_bf16_f32 v51, v54, v55
	v_exp_f32_e32 v56, v56
	v_exp_f32_e32 v57, v57
	v_exp_f32_e32 v58, v58
	s_waitcnt lgkmcnt(8)
	v_mfma_f32_32x32x16_bf16 v[64:79], v[108:111], v[140:143], v[64:79]
	ds_read_b128 v[108:111], v236 offset:20128
	v_add_f32_e32 v238, v56, v238
	v_exp_f32_e32 v59, v59
	v_add_f32_e32 v239, v57, v239
	v_exp_f32_e32 v60, v60
	v_add_f32_e32 v238, v58, v238
	s_waitcnt lgkmcnt(0)
	s_barrier
	v_mfma_f32_32x32x16_bf16 v[80:95], v[112:115], v[144:147], v[80:95]
	ds_read_b128 v[112:115], v197 offset:26624
	v_exp_f32_e32 v61, v61
	v_add_f32_e32 v239, v59, v239
	v_exp_f32_e32 v62, v62
	v_add_f32_e32 v238, v60, v238
	v_exp_f32_e32 v63, v63
	v_mfma_f32_32x32x16_bf16 v[64:79], v[116:119], v[144:147], v[64:79]
	ds_read_b128 v[116:119], v197 offset:31232
	v_add_f32_e32 v239, v61, v239
	v_cvt_pk_bf16_f32 v56, v56, v57
	v_add_f32_e32 v238, v62, v238
	v_cvt_pk_bf16_f32 v57, v58, v59
	v_add_f32_e32 v239, v63, v239
	v_mfma_f32_32x32x16_bf16 v[80:95], v[120:123], v[148:151], v[80:95]
	ds_read_b128 v[120:123], v197 offset:26656
	v_cvt_pk_bf16_f32 v58, v60, v61
	v_cvt_pk_bf16_f32 v59, v62, v63
	v_exp_f32_e32 v32, v32
	v_exp_f32_e32 v33, v33
	v_exp_f32_e32 v34, v34
	v_mfma_f32_32x32x16_bf16 v[64:79], v[124:127], v[148:151], v[64:79]
	ds_read_b128 v[124:127], v197 offset:31264
	v_add_f32_e32 v238, v32, v238
	v_exp_f32_e32 v35, v35
	v_add_f32_e32 v239, v33, v239
	v_exp_f32_e32 v36, v36
	v_add_f32_e32 v238, v34, v238
	v_mfma_f32_32x32x16_bf16 v[80:95], v[96:99], v[152:155], v[80:95]
	ds_read_b128 v[96:99], v197 offset:26688
	v_exp_f32_e32 v37, v37
	v_add_f32_e32 v239, v35, v239
	v_exp_f32_e32 v38, v38
	v_add_f32_e32 v238, v36, v238
	v_mfma_f32_32x32x16_bf16 v[64:79], v[100:103], v[152:155], v[64:79]
	ds_read_b128 v[100:103], v197 offset:31296
	v_exp_f32_e32 v39, v39
	v_add_f32_e32 v239, v37, v239
	v_cvt_pk_bf16_f32 v32, v32, v33
	v_add_f32_e32 v238, v38, v238
	v_mfma_f32_32x32x16_bf16 v[80:95], v[104:107], v[156:159], v[80:95]
	ds_read_b128 v[104:107], v197 offset:26720
	v_cvt_pk_bf16_f32 v33, v34, v35
	v_add_f32_e32 v239, v39, v239
	v_cvt_pk_bf16_f32 v34, v36, v37
	v_cvt_pk_bf16_f32 v35, v38, v39
	v_mfma_f32_32x32x16_bf16 v[64:79], v[108:111], v[156:159], v[64:79]
	ds_read_b128 v[108:111], v197 offset:31328
	v_exp_f32_e32 v40, v40
	v_exp_f32_e32 v41, v41
	v_exp_f32_e32 v42, v42
	v_add_f32_e32 v238, v40, v238
	s_waitcnt lgkmcnt(7)
	v_mfma_f32_32x32x16_bf16 v[16:31], v[112:115], v[48:51], v[16:31]
	ds_read_b128 v[112:115], v236 offset:64
	v_exp_f32_e32 v43, v43
	v_add_f32_e32 v239, v41, v239
	v_exp_f32_e32 v44, v44
	v_add_f32_e32 v238, v42, v238
	s_waitcnt lgkmcnt(7)
	v_mfma_f32_32x32x16_bf16 v[0:15], v[116:119], v[48:51], v[0:15]
	ds_read_b128 v[116:119], v236 offset:6720
	v_exp_f32_e32 v45, v45
	v_add_f32_e32 v239, v43, v239
	v_exp_f32_e32 v46, v46
	v_add_f32_e32 v238, v44, v238
	s_waitcnt lgkmcnt(7)
	v_mfma_f32_32x32x16_bf16 v[16:31], v[120:123], v[56:59], v[16:31]
	ds_read_b128 v[120:123], v236 offset:96
	v_exp_f32_e32 v47, v47
	v_add_f32_e32 v239, v45, v239
	v_cvt_pk_bf16_f32 v40, v40, v41
	v_add_f32_e32 v238, v46, v238
	s_waitcnt lgkmcnt(7)
	v_mfma_f32_32x32x16_bf16 v[0:15], v[124:127], v[56:59], v[0:15]
	ds_read_b128 v[124:127], v236 offset:6752
	v_cvt_pk_bf16_f32 v41, v42, v43
	v_add_f32_e32 v239, v47, v239
	v_cvt_pk_bf16_f32 v42, v44, v45
	v_cvt_pk_bf16_f32 v43, v46, v47
	s_waitcnt lgkmcnt(7)
	v_mfma_f32_32x32x16_bf16 v[16:31], v[96:99], v[32:35], v[16:31]
	ds_read_b128 v[96:99], v236
	v_max3_f32 v240, v80, v64, v81
	v_max3_f32 v241, v65, v82, v66
	v_max3_f32 v240, v83, v67, v240
	v_max3_f32 v241, v84, v68, v241
	s_waitcnt lgkmcnt(7)
	v_mfma_f32_32x32x16_bf16 v[0:15], v[100:103], v[32:35], v[0:15]
	ds_read_b128 v[100:103], v236 offset:6656
	v_max3_f32 v240, v85, v69, v240
	v_max3_f32 v241, v86, v70, v241
	v_max3_f32 v240, v87, v71, v240
	v_max3_f32 v241, v88, v72, v241
	s_waitcnt lgkmcnt(7)
	v_mfma_f32_32x32x16_bf16 v[16:31], v[104:107], v[40:43], v[16:31]
	ds_read_b128 v[104:107], v236 offset:32
	v_max3_f32 v240, v89, v73, v240
	v_max3_f32 v241, v90, v74, v241
	v_max3_f32 v240, v91, v75, v240
	v_max3_f32 v241, v92, v76, v241
	s_waitcnt lgkmcnt(7)
	v_mfma_f32_32x32x16_bf16 v[0:15], v[108:111], v[40:43], v[0:15]
	ds_read_b128 v[108:111], v236 offset:6688
	v_max3_f32 v240, v93, v77, v240
	v_max3_f32 v241, v94, v78, v241
	v_max3_f32 v240, v95, v79, v240
	v_max_f32_e32 v240, v240, v241
	v_cmp_lt_f32_e32 vcc, s65, v240
	s_cbranch_vccnz .Lmf_rareB
.Lmf_rareB_ret:
	s_waitcnt vmcnt(0)
	ds_write_b128 v250, v[160:163] offset:13312
	ds_write_b128 v251, v[164:167] offset:13312
	ds_write_b128 v252, v[168:171] offset:13312
	ds_write_b128 v194, v[172:175] offset:35840
	ds_write_b128 v196, v[176:179] offset:35840
	s_add_i32 s0, s31, 1
	s_cmp_ge_u32 s0, s19
	s_cbranch_scc1 .Lmf_skipKB
	v_mov_b32_e32 v160, s21
	v_mov_b32_e32 v161, s45
	v_mov_b32_e32 v162, s20
	v_mov_b32_e32 v163, s44
	v_cndmask_b32_e64 v169, v160, v161, s[12:13]
	v_cndmask_b32_e64 v168, v162, v163, s[12:13]
	v_lshl_add_u64 v[168:169], v[204:205], 1, v[168:169]
	v_cndmask_b32_e64 v165, v160, v161, s[10:11]
	v_cndmask_b32_e64 v164, v162, v163, s[10:11]
	v_lshl_add_u64 v[164:165], v[202:203], 1, v[164:165]
	v_cndmask_b32_e64 v167, v160, v161, s[8:9]
	v_cndmask_b32_e64 v166, v162, v163, s[8:9]
	v_lshl_add_u64 v[166:167], v[200:201], 1, v[166:167]
	global_load_dwordx4 v[168:171], v[168:169], off
	global_load_dwordx4 v[160:163], v[166:167], off
	global_load_dwordx4 v[164:167], v[164:165], off
	s_add_u32 s20, s20, 0x10000
	s_addc_u32 s21, s21, 0
	s_add_u32 s44, s44, 0x1000
	s_addc_u32 s45, s45, 0

; #define MFMA(a, b, c) __builtin_amdgcn_mfma_f32_32x32x16_bf16((a), (b), (c), 0, 0, 0)
; DI unsigned pack2(float a, float b) { f32x2v f = {a, b}; bf16x2v v = __builtin_convertvector(f, bf16x2v); return __builtin_bit_cast(unsigned, v); }
; DI float xhalf(float v) { return __shfl_xor(v, 32); }
;   template <int PAR>
;   DI void step(int t, f32x16 (&cur)[2], f32x16 (&nxt)[2]) {
;     if (t + 1 < nt) sstore_k(PAR ^ 1);
;     if (t > 0) sstore_v(PAR);
;     __syncthreads();
;     if (t + 1 < nt) qk(PAR ^ 1, nxt);
;     float mx = fmaxf(cur[0][0], cur[1][0]);
; #pragma unroll
;     for (int i = 1; i < 16; ++i) mx = fmaxf(fmaxf(cur[0][i], cur[1][i]), mx);
;     if (__builtin_amdgcn_ballot_w64(mx > ATT_THR) != 0ull) {
;       asm volatile("" ::: "memory");
;       mx = fmaxf(mx, xhalf(mx));
;       const float want = mref + fmaxf(mx, 0.f);
;       const float mn = __uint_as_float(pack2(want, 0.f) << 16);
;       const float d = mn - mref;
;       const float alpha = __builtin_amdgcn_exp2f(-d);
;       mref = mn;
;       l *= alpha;
; #pragma unroll
;       for (int a = 0; a < 2; ++a)
; #pragma unroll
;         for (int i = 0; i < 16; ++i) { o[a][i] *= alpha; cur[a][i] -= d; nxt[a][i] -= d; }
;       u32x4 q4 = {h == 0 ? (pack2(-mn, 0.f) & 0xffffu) : 0u, 0u, 0u, 0u};
;       qm = __builtin_bit_cast(bf16x8, q4);
;     }
;     float psum = 0.f;
; #pragma unroll
;     for (int kb2 = 0; kb2 < 2; ++kb2)
; #pragma unroll
;       for (int i = 0; i < 16; ++i) { const float pv = __builtin_amdgcn_exp2f(cur[kb2][i]); cur[kb2][i] = pv; psum += pv; }
;     l += psum;
;     if (t + 2 < nt) gload_k(t + 2);
;     if (t + 1 < nt) gload_v(t + 1);
;     const u16* vb = sV + PAR * VBUF + r * GP + h * 8;
; #pragma unroll
;     for (int kb2 = 0; kb2 < 2; ++kb2)
; #pragma unroll
;       for (int s2 = 0; s2 < 2; ++s2) {
;         u32x4 pk = {pack2(cur[kb2][8 * s2], cur[kb2][8 * s2 + 1]), pack2(cur[kb2][8 * s2 + 2], cur[kb2][8 * s2 + 3]),
;                     pack2(cur[kb2][8 * s2 + 4], cur[kb2][8 * s2 + 5]), pack2(cur[kb2][8 * s2 + 6], cur[kb2][8 * s2 + 7])};
;         const bf16x8 pf = __builtin_bit_cast(bf16x8, pk);
; #pragma unroll
;         for (int db = 0; db < 2; ++db) {
;           const bf16x8 a = *(const bf16x8*)(vb + db * 32 * GP + kb2 * 32 + s2 * 16);
;           o[db] = MFMA(a, pf, o[db]);
;         }
;       }
.Lm_skipKA:
	global_load_dwordx4 v[172:175], v[130:131], off offset:-128
	global_load_dwordx4 v[176:179], v[220:221], off offset:-128
	v_exp_f32_e32 v48, v48
	v_exp_f32_e32 v49, v49
	v_exp_f32_e32 v50, v50
	v_add_f32_e32 v238, v48, v238
	v_exp_f32_e32 v51, v51
	v_add_f32_e32 v239, v49, v239
	v_exp_f32_e32 v52, v52
	v_add_f32_e32 v238, v50, v238
	s_waitcnt lgkmcnt(8)
	v_mfma_f32_32x32x16_bf16 v[80:95], v[96:99], v[136:139], 0
	ds_read_b128 v[96:99], v236 offset:13440
	v_exp_f32_e32 v53, v53
	v_add_f32_e32 v239, v51, v239
	v_exp_f32_e32 v54, v54
	v_add_f32_e32 v238, v52, v238
	s_waitcnt lgkmcnt(8)
	v_mfma_f32_32x32x16_bf16 v[64:79], v[100:103], v[136:139], 0
	ds_read_b128 v[100:103], v236 offset:20096
	v_exp_f32_e32 v55, v55
	v_add_f32_e32 v239, v53, v239
	v_cvt_pk_bf16_f32 v48, v48, v49
	v_add_f32_e32 v238, v54, v238
	s_waitcnt lgkmcnt(8)
	v_mfma_f32_32x32x16_bf16 v[80:95], v[104:107], v[140:143], v[80:95]
	ds_read_b128 v[104:107], v236 offset:13472
	v_cvt_pk_bf16_f32 v49, v50, v51
	v_add_f32_e32 v239, v55, v239
	v_cvt_pk_bf16_f32 v50, v52, v53
	v_cvt_pk_bf16_f32 v51, v54, v55
	s_waitcnt lgkmcnt(8)
	v_mfma_f32_32x32x16_bf16 v[64:79], v[108:111], v[140:143], v[64:79]
	ds_read_b128 v[108:111], v236 offset:20128
	v_exp_f32_e32 v56, v56
	v_exp_f32_e32 v57, v57
	v_exp_f32_e32 v58, v58
	v_add_f32_e32 v238, v56, v238
	s_waitcnt lgkmcnt(0)
	s_barrier
	v_mfma_f32_32x32x16_bf16 v[80:95], v[112:115], v[144:147], v[80:95]
	ds_read_b128 v[112:115], v197 offset:26624
	v_exp_f32_e32 v59, v59
	v_add_f32_e32 v239, v57, v239
	v_exp_f32_e32 v60, v60
	v_add_f32_e32 v238, v58, v238
	v_mfma_f32_32x32x16_bf16 v[64:79], v[116:119], v[144:147], v[64:79]
	ds_read_b128 v[116:119], v197 offset:31232
	v_exp_f32_e32 v61, v61
	v_add_f32_e32 v239, v59, v239
	v_exp_f32_e32 v62, v62
	v_add_f32_e32 v238, v60, v238
	v_mfma_f32_32x32x16_bf16 v[80:95], v[120:123], v[148:151], v[80:95]
	ds_read_b128 v[120:123], v197 offset:26656
	v_exp_f32_e32 v63, v63
	v_add_f32_e32 v239, v61, v239
	v_cvt_pk_bf16_f32 v56, v56, v57
	v_add_f32_e32 v238, v62, v238
	v_mfma_f32_32x32x16_bf16 v[64:79], v[124:127], v[148:151], v[64:79]
	ds_read_b128 v[124:127], v197 offset:31264
	v_cvt_pk_bf16_f32 v57, v58, v59
	v_add_f32_e32 v239, v63, v239
	v_cvt_pk_bf16_f32 v58, v60, v61
	v_cvt_pk_bf16_f32 v59, v62, v63
	v_mfma_f32_32x32x16_bf16 v[80:95], v[96:99], v[152:155], v[80:95]
	ds_read_b128 v[96:99], v197 offset:26688
	v_exp_f32_e32 v32, v32
	v_exp_f32_e32 v33, v33
	v_exp_f32_e32 v34, v34
	v_add_f32_e32 v238, v32, v238
	v_mfma_f32_32x32x16_bf16 v[64:79], v[100:103], v[152:155], v[64:79]
	ds_read_b128 v[100:103], v197 offset:31296
	v_exp_f32_e32 v35, v35
	v_add_f32_e32 v239, v33, v239
	v_exp_f32_e32 v36, v36
	v_add_f32_e32 v238, v34, v238
	v_mfma_f32_32x32x16_bf16 v[80:95], v[104:107], v[156:159], v[80:95]
	ds_read_b128 v[104:107], v197 offset:26720
	v_exp_f32_e32 v37, v37
	v_add_f32_e32 v239, v35, v239
	v_exp_f32_e32 v38, v38
	v_add_f32_e32 v238, v36, v238
	v_mfma_f32_32x32x16_bf16 v[64:79], v[108:111], v[156:159], v[64:79]
	ds_read_b128 v[108:111], v197 offset:31328
	v_exp_f32_e32 v39, v39
	v_add_f32_e32 v239, v37, v239
	v_cvt_pk_bf16_f32 v32, v32, v33
	v_add_f32_e32 v238, v38, v238
	v_mfma_f32_32x32x16_bf16 v[80:95], v[132:135], v[180:183], v[80:95]
	v_cvt_pk_bf16_f32 v33, v34, v35
	v_add_f32_e32 v239, v39, v239
	v_cvt_pk_bf16_f32 v34, v36, v37
	v_cvt_pk_bf16_f32 v35, v38, v39
	v_mfma_f32_32x32x16_bf16 v[64:79], v[132:135], v[180:183], v[64:79]
	v_exp_f32_e32 v40, v40
	v_exp_f32_e32 v41, v41
	v_exp_f32_e32 v42, v42
	v_add_f32_e32 v238, v40, v238
	s_waitcnt lgkmcnt(7)
	v_mfma_f32_32x32x16_bf16 v[16:31], v[112:115], v[48:51], v[16:31]
	ds_read_b128 v[112:115], v236 offset:64
	v_exp_f32_e32 v43, v43
	v_add_f32_e32 v239, v41, v239
	v_exp_f32_e32 v44, v44
	v_add_f32_e32 v238, v42, v238
	s_waitcnt lgkmcnt(7)
	v_mfma_f32_32x32x16_bf16 v[0:15], v[116:119], v[48:51], v[0:15]
	ds_read_b128 v[116:119], v236 offset:6720
	v_exp_f32_e32 v45, v45
	v_add_f32_e32 v239, v43, v239
	v_exp_f32_e32 v46, v46
	v_add_f32_e32 v238, v44, v238
	s_waitcnt lgkmcnt(7)
	v_mfma_f32_32x32x16_bf16 v[16:31], v[120:123], v[56:59], v[16:31]
	ds_read_b128 v[120:123], v236 offset:96
	v_exp_f32_e32 v47, v47
	v_add_f32_e32 v239, v45, v239
	v_cvt_pk_bf16_f32 v40, v40, v41
	v_add_f32_e32 v238, v46, v238
	s_waitcnt lgkmcnt(7)
	v_mfma_f32_32x32x16_bf16 v[0:15], v[124:127], v[56:59], v[0:15]
	ds_read_b128 v[124:127], v236 offset:6752
	v_cvt_pk_bf16_f32 v41, v42, v43
	v_add_f32_e32 v239, v47, v239
	v_cvt_pk_bf16_f32 v42, v44, v45
	v_cvt_pk_bf16_f32 v43, v46, v47
	s_waitcnt lgkmcnt(7)
	v_mfma_f32_32x32x16_bf16 v[16:31], v[96:99], v[32:35], v[16:31]
	ds_read_b128 v[96:99], v236
	v_max3_f32 v240, v80, v64, v81
	v_max3_f32 v241, v65, v82, v66
	v_max3_f32 v240, v83, v67, v240
	v_max3_f32 v241, v84, v68, v241
	s_waitcnt lgkmcnt(7)
	v_mfma_f32_32x32x16_bf16 v[0:15], v[100:103], v[32:35], v[0:15]
	ds_read_b128 v[100:103], v236 offset:6656
	v_max3_f32 v240, v85, v69, v240
	v_max3_f32 v241, v86, v70, v241
	v_max3_f32 v240, v87, v71, v240
	v_max3_f32 v241, v88, v72, v241
	s_waitcnt lgkmcnt(7)
	v_mfma_f32_32x32x16_bf16 v[16:31], v[104:107], v[40:43], v[16:31]
	ds_read_b128 v[104:107], v236 offset:32
	v_max3_f32 v240, v89, v73, v240
	v_max3_f32 v241, v90, v74, v241
	v_max3_f32 v240, v91, v75, v240
	v_max3_f32 v241, v92, v76, v241
	s_waitcnt lgkmcnt(7)
	v_mfma_f32_32x32x16_bf16 v[0:15], v[108:111], v[40:43], v[0:15]
	ds_read_b128 v[108:111], v236 offset:6688
	v_max3_f32 v240, v93, v77, v240
	v_max3_f32 v241, v94, v78, v241
	v_max3_f32 v240, v95, v79, v240
	v_max_f32_e32 v240, v240, v241
	v_cmp_lt_f32_e32 vcc, s65, v240
	s_cbranch_vccnz .Lm_rareB
